# s15 + attention: s_setprio 1 from the first QK MFMA of a tile to its barrier, s_setprio 0 for the post-barrier VALU/LDS-write stretch
# speedup vs baseline: 1.0046x; 1.0046x over previous
; __device__ __forceinline__ void finishSM(f32x16& p0, f32x16& p1, float alpha, float& l_reg, bf16x8& pa0, bf16x8& pa1, bf16x8& pa2, bf16x8& pa3) {
;   for (int r = 0; r < 16; ++r) p1[r] = __builtin_amdgcn_exp2f(p1[r]);
;   float ps = 0; for (int r = 0; r < 16; ++r) ps += p0[r]; for (int r = 0; r < 16; ++r) ps += p1[r];
;   { auto rr = __builtin_amdgcn_permlane32_swap(__float_as_uint(ps), __float_as_uint(ps), false, false);
;     ps = __uint_as_float(rr[0]) + __uint_as_float(rr[1]); }
;   l_reg = l_reg * alpha + ps;
;     ...
;   PK4(p0, 0, pa0); PK4(p0, 8, pa1); PK4(p1, 0, pa2); PK4(p1, 8, pa3);
;     ...
; }
; __device__ __forceinline__ void qkt(f32x16& p0, f32x16& p1, const bf16* Ks, const bf16x8* qr, int r32, int hi) {
;   p0 = f32x16{}; p1 = f32x16{};
;   for (int d0 = 0; d0 < 8; ++d0) { int cb = (d0 * 16 + hi * 8) * 2;
;     bf16x8 b0 = *reinterpret_cast<const bf16x8*>((const char*)Ks + KSWZ(r32, cb));
;     bf16x8 b1 = *reinterpret_cast<const bf16x8*>((const char*)Ks + KSWZ(32 + r32, cb));
;     p0 = __builtin_amdgcn_mfma_f32_32x32x16_bf16(b0, qr[d0], p0, 0, 0, 0);
;     p1 = __builtin_amdgcn_mfma_f32_32x32x16_bf16(b1, qr[d0], p1, 0, 0, 0); }
.LBB0_602:
	ds_read_b128 v[64:67], v192 offset:49152
	ds_read_b128 v[68:71], v192 offset:57344
	ds_read_b128 v[242:245], v201 offset:49152
	ds_read_b128 v[246:249], v201 offset:57344
	v_exp_f32_e32 v160, v162
	v_add_f32_e32 v162, 0, v223
	s_waitcnt lgkmcnt(3)
	s_setprio 1
	v_mfma_f32_32x32x16_bf16 v[80:95], v[64:67], v[126:129], 0
	v_add_f32_e32 v162, v224, v162
	v_add_f32_e32 v162, v225, v162
	v_add_f32_e32 v162, v227, v162
	v_add_f32_e32 v162, v229, v162
	v_add_f32_e32 v162, v230, v162
	v_add_f32_e32 v162, v226, v162
	v_add_f32_e32 v162, v228, v162
	s_waitcnt lgkmcnt(2)
	v_mfma_f32_32x32x16_bf16 v[64:79], v[68:71], v[126:129], 0
	v_add_f32_e32 v162, v215, v162
	v_add_f32_e32 v162, v217, v162
	v_add_f32_e32 v162, v219, v162
	v_add_f32_e32 v162, v221, v162
	v_add_f32_e32 v162, v216, v162
	v_add_f32_e32 v162, v218, v162
	v_add_f32_e32 v162, v220, v162
	s_waitcnt lgkmcnt(1)
	v_mfma_f32_32x32x16_bf16 v[80:95], v[242:245], v[122:125], v[80:95]
	v_add_f32_e32 v162, v222, v162
	v_exp_f32_e32 v154, v164
	v_exp_f32_e32 v155, v165
	v_exp_f32_e32 v156, v172
	v_exp_f32_e32 v157, v173
	v_exp_f32_e32 v158, v168
	v_exp_f32_e32 v159, v169
	s_waitcnt lgkmcnt(0)
	v_mfma_f32_32x32x16_bf16 v[64:79], v[246:249], v[122:125], v[64:79]
	ds_read_b128 v[242:245], v200 offset:49152
	ds_read_b128 v[246:249], v200 offset:57344
	v_exp_f32_e32 v161, v163
	v_cvt_pk_bf16_f32 v164, v229, v230
	v_cvt_pk_bf16_f32 v163, v225, v227
	v_cvt_pk_bf16_f32 v165, v226, v228
	v_cvt_pk_bf16_f32 v168, v216, v218
	v_cvt_pk_bf16_f32 v169, v220, v222
	s_waitcnt lgkmcnt(1)
	v_mfma_f32_32x32x16_bf16 v[80:95], v[242:245], v[134:137], v[80:95]
	v_exp_f32_e32 v146, v176
	v_exp_f32_e32 v147, v177
	v_exp_f32_e32 v148, v174
	v_exp_f32_e32 v149, v175
	v_permlane32_swap_b32_e32 v163, v165
	s_waitcnt lgkmcnt(0)
	v_mfma_f32_32x32x16_bf16 v[64:79], v[246:249], v[134:137], v[64:79]
	ds_read_b128 v[242:245], v195 offset:49152
	ds_read_b128 v[246:249], v195 offset:57344
	v_add_f32_e32 v162, v146, v162
	v_add_f32_e32 v162, v147, v162
	v_add_f32_e32 v162, v148, v162
	v_exp_f32_e32 v150, v170
	s_waitcnt lgkmcnt(1)
	v_mfma_f32_32x32x16_bf16 v[80:95], v[242:245], v[130:133], v[80:95]
	v_exp_f32_e32 v151, v171
	v_exp_f32_e32 v152, v166
	v_exp_f32_e32 v153, v167
	v_add_f32_e32 v162, v149, v162
	s_waitcnt lgkmcnt(0)
	v_mfma_f32_32x32x16_bf16 v[64:79], v[246:249], v[130:133], v[64:79]
	ds_read_b128 v[242:245], v194 offset:49152
	ds_read_b128 v[246:249], v194 offset:57344
	v_add_f32_e32 v162, v150, v162
	v_add_f32_e32 v162, v151, v162
	v_add_f32_e32 v162, v152, v162
	v_add_f32_e32 v162, v153, v162
	s_waitcnt lgkmcnt(1)
	v_mfma_f32_32x32x16_bf16 v[80:95], v[242:245], v[118:121], v[80:95]
	v_add_f32_e32 v162, v154, v162
	v_add_f32_e32 v162, v155, v162
	v_add_f32_e32 v162, v156, v162
	v_add_f32_e32 v162, v157, v162
	s_waitcnt lgkmcnt(0)
	v_mfma_f32_32x32x16_bf16 v[64:79], v[246:249], v[118:121], v[64:79]
	ds_read_b128 v[242:245], v193 offset:49152
	ds_read_b128 v[246:249], v193 offset:57344
	v_add_f32_e32 v162, v158, v162
	v_add_f32_e32 v162, v159, v162
	v_add_f32_e32 v162, v160, v162
	v_add_f32_e32 v211, v161, v162
	s_waitcnt lgkmcnt(1)
	v_mfma_f32_32x32x16_bf16 v[80:95], v[242:245], v[114:117], v[80:95]
	v_mov_b32_e32 v212, v211
	v_cvt_pk_bf16_f32 v162, v223, v224
	s_nop 0
	v_permlane32_swap_b32_e32 v211, v212
	s_waitcnt lgkmcnt(0)
	v_mfma_f32_32x32x16_bf16 v[64:79], v[246:249], v[114:117], v[64:79]
	ds_read_b128 v[242:245], v207 offset:49152
	ds_read_b128 v[246:249], v207 offset:57344
	v_permlane32_swap_b32_e32 v162, v164
	v_cvt_pk_bf16_f32 v166, v215, v217
	v_cvt_pk_bf16_f32 v167, v219, v221
	v_cvt_pk_bf16_f32 v170, v146, v147
	s_waitcnt lgkmcnt(1)
	v_mfma_f32_32x32x16_bf16 v[80:95], v[242:245], v[110:113], v[80:95]
	v_cvt_pk_bf16_f32 v171, v148, v149
	v_cvt_pk_bf16_f32 v172, v150, v151
	v_cvt_pk_bf16_f32 v173, v152, v153
	v_cvt_pk_bf16_f32 v174, v154, v155
	s_waitcnt lgkmcnt(0)
	v_mfma_f32_32x32x16_bf16 v[64:79], v[246:249], v[110:113], v[64:79]
	ds_read_b128 v[242:245], v206 offset:49152
	ds_read_b128 v[246:249], v206 offset:57344
	v_cvt_pk_bf16_f32 v175, v156, v157
	v_cvt_pk_bf16_f32 v176, v158, v159
	v_cvt_pk_bf16_f32 v177, v160, v161
	s_waitcnt lgkmcnt(1)
	v_mfma_f32_32x32x16_bf16 v[80:95], v[242:245], v[106:109], v[80:95]
	v_permlane32_swap_b32_e32 v166, v168
	v_permlane32_swap_b32_e32 v167, v169
	v_permlane32_swap_b32_e32 v170, v172
	s_waitcnt lgkmcnt(0)
	v_mfma_f32_32x32x16_bf16 v[64:79], v[246:249], v[106:109], v[64:79]
	v_permlane32_swap_b32_e32 v171, v173
	v_permlane32_swap_b32_e32 v174, v176
	v_permlane32_swap_b32_e32 v175, v177
	v_add_co_u32_e32 v146, vcc, s69, v182
	s_mov_b32 s8, 0xffff0000
	s_nop 0
	v_addc_co_u32_e32 v147, vcc, -1, v183, vcc
	v_add_co_u32_e32 v150, vcc, s8, v182
	s_mov_b32 s8, 0xff6e8000
	s_nop 0
	v_addc_co_u32_e32 v151, vcc, -1, v183, vcc
	v_add_co_u32_e32 v154, vcc, s8, v182
	s_mov_b32 s8, 0xff6f0000
	s_nop 0
	v_addc_co_u32_e32 v155, vcc, -1, v183, vcc
	v_add_co_u32_e32 v158, vcc, s8, v182
	global_load_dwordx4 v[146:149], v[146:147], off
	s_nop 0
	global_load_dwordx4 v[150:153], v[150:151], off
	v_addc_co_u32_e32 v159, vcc, -1, v183, vcc
	global_load_dwordx4 v[154:157], v[154:155], off
	s_nop 0
	global_load_dwordx4 v[158:161], v[158:159], off
	ds_read_b64_tr_b16 v[214:215], v179 offset:0
	ds_read_b64_tr_b16 v[216:217], v179 offset:0x800
	ds_read_b64_tr_b16 v[218:219], v179 offset:0x1000
	ds_read_b64_tr_b16 v[220:221], v179 offset:0x1800
	ds_read_b64_tr_b16 v[222:223], v179 offset:0x2000
	ds_read_b64_tr_b16 v[224:225], v179 offset:0x2800
	ds_read_b64_tr_b16 v[226:227], v179 offset:0x3000
	ds_read_b64_tr_b16 v[228:229], v179 offset:0x3800
	s_waitcnt vmcnt(4)
; #define SBAR() __builtin_amdgcn_sched_barrier(0)
; __device__ __forceinline__ void partialSM(f32x16& p0, f32x16& p1, float& m_reg, float& mn, float& alpha) {
;   constexpr float C = SCALE * 1.4426950408889634f;
;   float pmax = p0[0]; for (int r = 1; r < 16; ++r) pmax = fmaxf(pmax, p0[r]); for (int r = 0; r < 16; ++r) pmax = fmaxf(pmax, p1[r]);
;   { auto rr = __builtin_amdgcn_permlane32_swap(__float_as_uint(pmax), __float_as_uint(pmax), false, false);
;     pmax = fmaxf(__uint_as_float(rr[0]), __uint_as_float(rr[1])); }
;   if (__builtin_expect(__all(pmax - m_reg <= THR / SCALE), 1)) { mn = m_reg; alpha = 1.f; }
;   else { mn = fmaxf(m_reg, pmax); alpha = __builtin_amdgcn_exp2f((m_reg - mn) * C); m_reg = mn; }
;   float mnC = -mn * C;
;   for (int r = 0; r < 16; ++r) p0[r] = fmaf(p0[r], C, mnC); for (int r = 0; r < 16; ++r) p1[r] = fmaf(p1[r], C, mnC);
;   for (int r = 0; r < 16; ++r) p0[r] = __builtin_amdgcn_exp2f(p0[r]);
; template <int D0> __device__ __forceinline__ void pv_one(f32x16& od, int vb, bf16x8 pa0, bf16x8 pa1, bf16x8 pa2, bf16x8 pa3) {
;   const s16x4 l0 = tr_read<v_rd_off(D0, 0, 0)>(vb), h0 = tr_read<v_rd_off(D0, 0, 1)>(vb), l1 = tr_read<v_rd_off(D0, 1, 0)>(vb), h1 = tr_read<v_rd_off(D0, 1, 1)>(vb);
;   const s16x4 l2 = tr_read<v_rd_off(D0, 2, 0)>(vb), h2 = tr_read<v_rd_off(D0, 2, 1)>(vb), l3 = tr_read<v_rd_off(D0, 3, 0)>(vb), h3 = tr_read<v_rd_off(D0, 3, 1)>(vb);
;   asm volatile("s_waitcnt lgkmcnt(0)" ::: "memory"); SBAR();
;     ...
;   od = __builtin_amdgcn_mfma_f32_32x32x16_bf16(pa0, PK(l0, h0), od, 0, 0, 0);
;   od = __builtin_amdgcn_mfma_f32_32x32x16_bf16(pa1, PK(l1, h1), od, 0, 0, 0);
;   od = __builtin_amdgcn_mfma_f32_32x32x16_bf16(pa2, PK(l2, h2), od, 0, 0, 0);
;   od = __builtin_amdgcn_mfma_f32_32x32x16_bf16(pa3, PK(l3, h3), od, 0, 0, 0);
;     ...
; }
; __device__ __forceinline__ void pv_d0(f32x16* o, int vb, bf16x8 pa0, bf16x8 pa1, bf16x8 pa2, bf16x8 pa3) {
;   pv_one<0>(o[0], vb, pa0, pa1, pa2, pa3); pv_one<1>(o[1], vb, pa0, pa1, pa2, pa3); pv_one<2>(o[2], vb, pa0, pa1, pa2, pa3); pv_one<3>(o[3], vb, pa0, pa1, pa2, pa3);
	ds_write_b128 v202, v[102:105] offset:32768
	ds_write_b128 v203, v[142:145] offset:32768
	s_waitcnt lgkmcnt(2)
	s_nop 0
	v_mfma_f32_32x32x16_bf16 v[0:15], v[162:165], v[214:217], v[0:15]
	ds_read_b64_tr_b16 v[214:215], v179 offset:0x200
	ds_read_b64_tr_b16 v[216:217], v179 offset:0xa00
	v_max_f32_e32 v232, v81, v81
	v_max_f32_e32 v233, v80, v80
	v_max_f32_e32 v232, v233, v232
	v_max3_f32 v232, v232, v82, v83
	v_max3_f32 v232, v232, v84, v85
	v_max3_f32 v232, v232, v86, v87
	v_mfma_f32_32x32x16_bf16 v[0:15], v[166:169], v[218:221], v[0:15]
	ds_read_b64_tr_b16 v[218:219], v179 offset:0x1200
	ds_read_b64_tr_b16 v[220:221], v179 offset:0x1a00
	v_max3_f32 v232, v232, v88, v89
	v_max3_f32 v232, v232, v90, v91
	v_max3_f32 v232, v232, v92, v93
	v_max3_f32 v232, v232, v94, v95
	v_max3_f32 v232, v232, v64, v65
	v_max3_f32 v232, v232, v66, v67
	v_mfma_f32_32x32x16_bf16 v[0:15], v[170:173], v[222:225], v[0:15]
	ds_read_b64_tr_b16 v[222:223], v179 offset:0x2200
	ds_read_b64_tr_b16 v[224:225], v179 offset:0x2a00
	v_max3_f32 v232, v232, v68, v69
	v_max3_f32 v232, v232, v70, v71
	v_max3_f32 v232, v232, v72, v73
	v_max3_f32 v232, v232, v74, v75
	v_max3_f32 v232, v232, v76, v77
	v_max3_f32 v232, v232, v78, v79
	v_mfma_f32_32x32x16_bf16 v[0:15], v[174:177], v[226:229], v[0:15]
	ds_read_b64_tr_b16 v[226:227], v179 offset:0x3200
	ds_read_b64_tr_b16 v[228:229], v179 offset:0x3a00
	v_mov_b32_e32 v233, v232
	s_nop 1
	v_permlane32_swap_b32_e32 v232, v233
	v_max_f32_e32 v233, v233, v233
	v_max_f32_e32 v232, v232, v232
	v_max_f32_e32 v232, v232, v233
	s_waitcnt lgkmcnt(0)
	v_mfma_f32_32x32x16_bf16 v[48:63], v[162:165], v[214:217], v[48:63]
	ds_read_b64_tr_b16 v[214:215], v179 offset:0x400
	ds_read_b64_tr_b16 v[216:217], v179 offset:0xc00
	v_sub_f32_e32 v233, v232, v210
	v_cmp_ge_f32_e32 vcc, s68, v233
	v_max_f32_e32 v233, v210, v210
	v_max_f32_e32 v232, v233, v232
	v_sub_f32_e32 v233, v210, v232
	v_mul_f32_e32 v233, 0x3e0293ee, v233
	v_mfma_f32_32x32x16_bf16 v[48:63], v[166:169], v[218:221], v[48:63]
	ds_read_b64_tr_b16 v[218:219], v179 offset:0x1400
	ds_read_b64_tr_b16 v[220:221], v179 offset:0x1c00
	s_cmp_eq_u64 vcc, exec
	s_cselect_b64 s[8:9], -1, 0
	v_exp_f32_e32 v233, v233
	v_mfma_f32_32x32x16_bf16 v[48:63], v[170:173], v[222:225], v[48:63]
	ds_read_b64_tr_b16 v[222:223], v179 offset:0x2400
	ds_read_b64_tr_b16 v[224:225], v179 offset:0x2c00
	v_cndmask_b32_e64 v210, v232, v210, s[8:9]
	v_mul_f32_e32 v213, 0xbe0293ee, v210
	v_fmamk_f32 v80, v80, 0x3e0293ee, v213
	v_fmamk_f32 v81, v81, 0x3e0293ee, v213
	v_fmamk_f32 v82, v82, 0x3e0293ee, v213
	v_fmamk_f32 v83, v83, 0x3e0293ee, v213
	v_mfma_f32_32x32x16_bf16 v[48:63], v[174:177], v[226:229], v[48:63]
	ds_read_b64_tr_b16 v[226:227], v179 offset:0x3400
	ds_read_b64_tr_b16 v[228:229], v179 offset:0x3c00
	v_fmamk_f32 v84, v84, 0x3e0293ee, v213
	v_fmamk_f32 v85, v85, 0x3e0293ee, v213
	v_fmamk_f32 v86, v86, 0x3e0293ee, v213
	v_fmamk_f32 v87, v87, 0x3e0293ee, v213
	v_fmamk_f32 v88, v88, 0x3e0293ee, v213
	v_fmamk_f32 v89, v89, 0x3e0293ee, v213
	s_waitcnt lgkmcnt(0)
	v_mfma_f32_32x32x16_bf16 v[32:47], v[162:165], v[214:217], v[32:47]
	ds_read_b64_tr_b16 v[214:215], v179 offset:0x600
	ds_read_b64_tr_b16 v[216:217], v179 offset:0xe00
	v_fmamk_f32 v90, v90, 0x3e0293ee, v213
	v_fmamk_f32 v91, v91, 0x3e0293ee, v213
	v_fmamk_f32 v92, v92, 0x3e0293ee, v213
	v_fmamk_f32 v93, v93, 0x3e0293ee, v213
	v_fmamk_f32 v94, v94, 0x3e0293ee, v213
	v_fmamk_f32 v95, v95, 0x3e0293ee, v213
	v_mfma_f32_32x32x16_bf16 v[32:47], v[166:169], v[218:221], v[32:47]
	ds_read_b64_tr_b16 v[218:219], v179 offset:0x1600
	ds_read_b64_tr_b16 v[220:221], v179 offset:0x1e00
	v_exp_f32_e32 v80, v80
	v_exp_f32_e32 v81, v81
	v_exp_f32_e32 v82, v82
	v_mfma_f32_32x32x16_bf16 v[32:47], v[170:173], v[222:225], v[32:47]
	ds_read_b64_tr_b16 v[222:223], v179 offset:0x2600
	ds_read_b64_tr_b16 v[224:225], v179 offset:0x2e00
	v_exp_f32_e32 v83, v83
	v_exp_f32_e32 v84, v84
	v_exp_f32_e32 v85, v85
	v_mfma_f32_32x32x16_bf16 v[32:47], v[174:177], v[226:229], v[32:47]
	ds_read_b64_tr_b16 v[226:227], v179 offset:0x3600
	ds_read_b64_tr_b16 v[228:229], v179 offset:0x3e00
	v_exp_f32_e32 v86, v86
	v_exp_f32_e32 v87, v87
	v_exp_f32_e32 v88, v88
	s_waitcnt lgkmcnt(0)
	v_mfma_f32_32x32x16_bf16 v[16:31], v[162:165], v[214:217], v[16:31]
	v_exp_f32_e32 v89, v89
	v_exp_f32_e32 v90, v90
	v_exp_f32_e32 v91, v91
	v_mfma_f32_32x32x16_bf16 v[16:31], v[166:169], v[218:221], v[16:31]
	v_exp_f32_e32 v92, v92
	v_exp_f32_e32 v93, v93
	v_mfma_f32_32x32x16_bf16 v[16:31], v[170:173], v[222:225], v[16:31]
	v_exp_f32_e32 v94, v94
	v_exp_f32_e32 v95, v95
	v_mfma_f32_32x32x16_bf16 v[16:31], v[174:177], v[226:229], v[16:31]
	s_barrier
	s_setprio 0
	s_waitcnt vmcnt(4)
	v_cndmask_b32_e64 v214, v233, 1.0, s[8:9]
	v_cmp_gt_f32_e32 vcc, 1.0, v214
	s_waitcnt vmcnt(7)
	ds_write_b128 v204, v[98:101]
	s_waitcnt vmcnt(6)
	ds_write_b128 v205, v[138:141]
	s_cbranch_vccz .LBB0_606
	s_and_saveexec_b64 s[12:13], s[6:7]
	ds_write_b32 v189, v214 offset:128
	s_or_b64 exec, exec, s[12:13]
	s_waitcnt lgkmcnt(0)
	v_add_u32_e32 v163, v181, v180
	ds_read_b128 v[164:167], v163 offset:224
	ds_read_b128 v[168:171], v163 offset:192
	ds_read_b128 v[172:175], v163 offset:160
	ds_read_b128 v[216:219], v163 offset:128
	s_waitcnt lgkmcnt(3)
	v_pk_mul_f32 v[12:13], v[12:13], v[164:165]
	s_waitcnt lgkmcnt(2)
	v_pk_mul_f32 v[8:9], v[8:9], v[168:169]
	s_waitcnt lgkmcnt(1)
	v_pk_mul_f32 v[4:5], v[4:5], v[172:173]
	v_pk_mul_f32 v[14:15], v[14:15], v[166:167]
	v_pk_mul_f32 v[10:11], v[10:11], v[170:171]
	v_pk_mul_f32 v[6:7], v[6:7], v[174:175]
	s_waitcnt lgkmcnt(0)
	v_pk_mul_f32 v[2:3], v[2:3], v[218:219]
	v_pk_mul_f32 v[0:1], v[0:1], v[216:217]
	v_pk_mul_f32 v[60:61], v[60:61], v[164:165]
	v_pk_mul_f32 v[56:57], v[56:57], v[168:169]
	v_pk_mul_f32 v[52:53], v[52:53], v[172:173]
	v_pk_mul_f32 v[62:63], v[62:63], v[166:167]
	v_pk_mul_f32 v[58:59], v[58:59], v[170:171]
	v_pk_mul_f32 v[54:55], v[54:55], v[174:175]
	v_pk_mul_f32 v[50:51], v[50:51], v[218:219]
	v_pk_mul_f32 v[48:49], v[48:49], v[216:217]
	v_pk_mul_f32 v[44:45], v[44:45], v[164:165]
	v_pk_mul_f32 v[40:41], v[40:41], v[168:169]
	v_pk_mul_f32 v[36:37], v[36:37], v[172:173]
	v_pk_mul_f32 v[46:47], v[46:47], v[166:167]
	v_pk_mul_f32 v[42:43], v[42:43], v[170:171]
	v_pk_mul_f32 v[38:39], v[38:39], v[174:175]
	v_pk_mul_f32 v[34:35], v[34:35], v[218:219]
	v_pk_mul_f32 v[32:33], v[32:33], v[216:217]
	v_pk_mul_f32 v[28:29], v[28:29], v[164:165]
	v_pk_mul_f32 v[24:25], v[24:25], v[168:169]
	v_pk_mul_f32 v[20:21], v[20:21], v[172:173]
	v_pk_mul_f32 v[30:31], v[30:31], v[166:167]
	v_pk_mul_f32 v[26:27], v[26:27], v[170:171]
	v_pk_mul_f32 v[22:23], v[22:23], v[174:175]
	v_pk_mul_f32 v[18:19], v[18:19], v[218:219]
	v_pk_mul_f32 v[16:17], v[16:17], v[216:217]
; __device__ __forceinline__ void partialSM(f32x16& p0, f32x16& p1, float& m_reg, float& mn, float& alpha) {
;     ...
;   float mnC = -mn * C;
;   for (int r = 0; r < 16; ++r) p0[r] = fmaf(p0[r], C, mnC); for (int r = 0; r < 16; ++r) p1[r] = fmaf(p1[r], C, mnC);
;   for (int r = 0; r < 16; ++r) p0[r] = __builtin_amdgcn_exp2f(p0[r]);
; }
; __device__ __forceinline__ void finishSM(f32x16& p0, f32x16& p1, float alpha, float& l_reg, bf16x8& pa0, bf16x8& pa1, bf16x8& pa2, bf16x8& pa3) {
;   for (int r = 0; r < 16; ++r) p1[r] = __builtin_amdgcn_exp2f(p1[r]);
;   float ps = 0; for (int r = 0; r < 16; ++r) ps += p0[r]; for (int r = 0; r < 16; ++r) ps += p1[r];
;   { auto rr = __builtin_amdgcn_permlane32_swap(__float_as_uint(ps), __float_as_uint(ps), false, false);
;     ps = __uint_as_float(rr[0]) + __uint_as_float(rr[1]); }
;   l_reg = l_reg * alpha + ps;
;     ...
;   PK4(p0, 0, pa0); PK4(p0, 8, pa1); PK4(p1, 0, pa2); PK4(p1, 8, pa3);
;     ...
; }
; __device__ __forceinline__ void qkt(f32x16& p0, f32x16& p1, const bf16* Ks, const bf16x8* qr, int r32, int hi) {
;   p0 = f32x16{}; p1 = f32x16{};
;   for (int d0 = 0; d0 < 8; ++d0) { int cb = (d0 * 16 + hi * 8) * 2;
;     bf16x8 b0 = *reinterpret_cast<const bf16x8*>((const char*)Ks + KSWZ(r32, cb));
;     bf16x8 b1 = *reinterpret_cast<const bf16x8*>((const char*)Ks + KSWZ(32 + r32, cb));
;     p0 = __builtin_amdgcn_mfma_f32_32x32x16_bf16(b0, qr[d0], p0, 0, 0, 0);
;     p1 = __builtin_amdgcn_mfma_f32_32x32x16_bf16(b1, qr[d0], p1, 0, 0, 0); }
.LBB0_606:
	v_mov_b32_e32 v162, v80
	v_mov_b32_e32 v163, v81
	v_mov_b32_e32 v164, v82
	v_mov_b32_e32 v175, v83
	v_mov_b32_e32 v176, v84
	v_mov_b32_e32 v177, v85
	v_mov_b32_e32 v165, v86
	v_mov_b32_e32 v174, v87
	v_mov_b32_e32 v166, v88
	v_mov_b32_e32 v167, v89
	v_mov_b32_e32 v172, v90
	v_mov_b32_e32 v173, v91
	v_mov_b32_e32 v168, v92
	v_mov_b32_e32 v169, v93
	v_mov_b32_e32 v170, v94
	v_mov_b32_e32 v171, v95
	v_fmamk_f32 v223, v64, 0x3e0293ee, v213
	v_fmamk_f32 v224, v65, 0x3e0293ee, v213
	v_fmamk_f32 v225, v66, 0x3e0293ee, v213
	v_fmamk_f32 v226, v67, 0x3e0293ee, v213
	v_fmamk_f32 v227, v68, 0x3e0293ee, v213
	v_fmamk_f32 v216, v69, 0x3e0293ee, v213
	v_fmamk_f32 v217, v70, 0x3e0293ee, v213
	v_fmamk_f32 v218, v71, 0x3e0293ee, v213
	v_fmamk_f32 v219, v72, 0x3e0293ee, v213
	v_fmamk_f32 v220, v73, 0x3e0293ee, v213
	v_fmamk_f32 v221, v74, 0x3e0293ee, v213
	v_fmamk_f32 v222, v75, 0x3e0293ee, v213
	v_fmamk_f32 v215, v76, 0x3e0293ee, v213
	v_fmamk_f32 v228, v77, 0x3e0293ee, v213
	v_fmamk_f32 v229, v78, 0x3e0293ee, v213
	v_fmac_f32_e32 v213, 0x3e0293ee, v79
	ds_read_b128 v[64:67], v192 offset:32768
	ds_read_b128 v[68:71], v192 offset:40960
	ds_read_b128 v[242:245], v201 offset:32768
	ds_read_b128 v[246:249], v201 offset:40960
	v_add_f32_e32 v230, 0, v162
	v_add_f32_e32 v230, v163, v230
	s_waitcnt lgkmcnt(3)
	s_setprio 1
	v_mfma_f32_32x32x16_bf16 v[80:95], v[64:67], v[126:129], 0
	v_add_f32_e32 v230, v164, v230
	v_add_f32_e32 v230, v175, v230
	v_add_f32_e32 v230, v176, v230
	v_add_f32_e32 v230, v177, v230
	v_add_f32_e32 v230, v165, v230
	v_add_f32_e32 v230, v174, v230
	v_add_f32_e32 v230, v166, v230
	s_waitcnt lgkmcnt(2)
	v_mfma_f32_32x32x16_bf16 v[64:79], v[68:71], v[126:129], 0
	v_add_f32_e32 v230, v167, v230
	v_add_f32_e32 v230, v172, v230
	v_add_f32_e32 v230, v173, v230
	v_exp_f32_e32 v223, v223
	v_add_f32_e32 v230, v168, v230
	v_exp_f32_e32 v224, v224
	v_add_f32_e32 v230, v169, v230
	s_waitcnt lgkmcnt(1)
	v_mfma_f32_32x32x16_bf16 v[80:95], v[242:245], v[122:125], v[80:95]
	v_exp_f32_e32 v225, v225
	v_add_f32_e32 v230, v170, v230
	v_exp_f32_e32 v226, v226
	v_add_f32_e32 v230, v171, v230
	v_exp_f32_e32 v227, v227
	v_add_f32_e32 v230, v223, v230
	v_exp_f32_e32 v216, v216
	s_waitcnt lgkmcnt(0)
	v_mfma_f32_32x32x16_bf16 v[64:79], v[246:249], v[122:125], v[64:79]
	ds_read_b128 v[242:245], v200 offset:32768
	ds_read_b128 v[246:249], v200 offset:40960
	v_add_f32_e32 v230, v224, v230
	v_exp_f32_e32 v217, v217
	v_add_f32_e32 v230, v225, v230
	v_exp_f32_e32 v218, v218
	v_add_f32_e32 v230, v226, v230
	v_exp_f32_e32 v219, v219
	s_waitcnt lgkmcnt(1)
	v_mfma_f32_32x32x16_bf16 v[80:95], v[242:245], v[134:137], v[80:95]
	v_add_f32_e32 v230, v227, v230
	v_exp_f32_e32 v220, v220
	v_add_f32_e32 v230, v216, v230
	v_exp_f32_e32 v221, v221
	v_add_f32_e32 v230, v217, v230
	v_exp_f32_e32 v222, v222
	v_add_f32_e32 v230, v218, v230
	s_waitcnt lgkmcnt(0)
	v_mfma_f32_32x32x16_bf16 v[64:79], v[246:249], v[134:137], v[64:79]
	ds_read_b128 v[242:245], v195 offset:32768
	ds_read_b128 v[246:249], v195 offset:40960
	v_exp_f32_e32 v215, v215
	v_add_f32_e32 v230, v219, v230
	v_exp_f32_e32 v228, v228
	v_add_f32_e32 v230, v220, v230
	v_exp_f32_e32 v229, v229
	v_add_f32_e32 v230, v221, v230
	s_waitcnt lgkmcnt(1)
	v_mfma_f32_32x32x16_bf16 v[80:95], v[242:245], v[130:133], v[80:95]
	v_exp_f32_e32 v213, v213
	v_add_f32_e32 v230, v222, v230
	v_add_f32_e32 v230, v215, v230
	v_add_f32_e32 v230, v228, v230
	v_add_f32_e32 v230, v229, v230
	v_add_f32_e32 v231, v213, v230
	v_mov_b32_e32 v241, v231
	s_waitcnt lgkmcnt(0)
	v_mfma_f32_32x32x16_bf16 v[64:79], v[246:249], v[130:133], v[64:79]
	ds_read_b128 v[242:245], v194 offset:32768
	ds_read_b128 v[246:249], v194 offset:40960
	v_cvt_pk_bf16_f32 v162, v162, v163
	v_cvt_pk_bf16_f32 v163, v164, v175
	v_cvt_pk_bf16_f32 v164, v176, v177
	v_cvt_pk_bf16_f32 v165, v165, v174
	v_cvt_pk_bf16_f32 v166, v166, v167
	v_cvt_pk_bf16_f32 v167, v172, v173
	s_waitcnt lgkmcnt(1)
	v_mfma_f32_32x32x16_bf16 v[80:95], v[242:245], v[118:121], v[80:95]
	v_cvt_pk_bf16_f32 v168, v168, v169
	v_cvt_pk_bf16_f32 v169, v170, v171
	v_cvt_pk_bf16_f32 v170, v223, v224
	v_cvt_pk_bf16_f32 v171, v225, v226
	v_cvt_pk_bf16_f32 v172, v227, v216
	v_cvt_pk_bf16_f32 v173, v217, v218
	v_cvt_pk_bf16_f32 v174, v219, v220
	s_waitcnt lgkmcnt(0)
	v_mfma_f32_32x32x16_bf16 v[64:79], v[246:249], v[118:121], v[64:79]
	ds_read_b128 v[242:245], v193 offset:32768
	ds_read_b128 v[246:249], v193 offset:40960
	v_cvt_pk_bf16_f32 v175, v221, v222
	v_cvt_pk_bf16_f32 v176, v215, v228
	v_cvt_pk_bf16_f32 v177, v229, v213
	v_permlane32_swap_b32_e32 v231, v241
	v_permlane32_swap_b32_e32 v162, v164
	s_waitcnt lgkmcnt(1)
	v_mfma_f32_32x32x16_bf16 v[80:95], v[242:245], v[114:117], v[80:95]
	v_permlane32_swap_b32_e32 v163, v165
	v_permlane32_swap_b32_e32 v166, v168
	v_permlane32_swap_b32_e32 v167, v169
	v_permlane32_swap_b32_e32 v170, v172
	s_waitcnt lgkmcnt(0)
	v_mfma_f32_32x32x16_bf16 v[64:79], v[246:249], v[114:117], v[64:79]
	ds_read_b128 v[242:245], v207 offset:32768
	ds_read_b128 v[246:249], v207 offset:40960
	v_permlane32_swap_b32_e32 v171, v173
	v_permlane32_swap_b32_e32 v174, v176
	v_permlane32_swap_b32_e32 v175, v177
	s_waitcnt lgkmcnt(1)
	v_mfma_f32_32x32x16_bf16 v[80:95], v[242:245], v[110:113], v[80:95]
	s_waitcnt lgkmcnt(0)
	v_mfma_f32_32x32x16_bf16 v[64:79], v[246:249], v[110:113], v[64:79]
	ds_read_b128 v[242:245], v206 offset:32768
	ds_read_b128 v[246:249], v206 offset:40960
	s_waitcnt lgkmcnt(1)
	v_mfma_f32_32x32x16_bf16 v[80:95], v[242:245], v[106:109], v[80:95]
	s_waitcnt lgkmcnt(0)
	v_mfma_f32_32x32x16_bf16 v[64:79], v[246:249], v[106:109], v[64:79]
	s_cmp_ge_u32 s40, s41
	s_cselect_b64 s[12:13], -1, 0
	s_and_b64 vcc, exec, s[12:13]
	s_cbranch_vccnz .LBB0_608
	v_add_co_u32_e32 v98, vcc, 0xffff8000, v182
	s_nop 1
	v_addc_co_u32_e32 v99, vcc, -1, v183, vcc
	v_add_co_u32_e32 v102, vcc, 0xff6f8000, v182
	s_nop 1
	v_addc_co_u32_e32 v103, vcc, -1, v183, vcc
	v_add_co_u32_e32 v142, vcc, 0xff700000, v182
	global_load_dwordx4 v[98:101], v[98:99], off
	s_nop 0
	global_load_dwordx4 v[102:105], v[102:103], off
	v_addc_co_u32_e32 v143, vcc, -1, v183, vcc
	global_load_dwordx4 v[138:141], v[182:183], off
	s_nop 0
	global_load_dwordx4 v[142:145], v[142:143], off

; #define SBAR() __builtin_amdgcn_sched_barrier(0)
; __device__ __forceinline__ void partialSM(f32x16& p0, f32x16& p1, float& m_reg, float& mn, float& alpha) {
;   constexpr float C = SCALE * 1.4426950408889634f;
;   float pmax = p0[0]; for (int r = 1; r < 16; ++r) pmax = fmaxf(pmax, p0[r]); for (int r = 0; r < 16; ++r) pmax = fmaxf(pmax, p1[r]);
;   { auto rr = __builtin_amdgcn_permlane32_swap(__float_as_uint(pmax), __float_as_uint(pmax), false, false);
;     pmax = fmaxf(__uint_as_float(rr[0]), __uint_as_float(rr[1])); }
;   if (__builtin_expect(__all(pmax - m_reg <= THR / SCALE), 1)) { mn = m_reg; alpha = 1.f; }
;   else { mn = fmaxf(m_reg, pmax); alpha = __builtin_amdgcn_exp2f((m_reg - mn) * C); m_reg = mn; }
;   float mnC = -mn * C;
;   for (int r = 0; r < 16; ++r) p0[r] = fmaf(p0[r], C, mnC); for (int r = 0; r < 16; ++r) p1[r] = fmaf(p1[r], C, mnC);
;   for (int r = 0; r < 16; ++r) p0[r] = __builtin_amdgcn_exp2f(p0[r]);
; template <int D0> __device__ __forceinline__ void pv_one(f32x16& od, int vb, bf16x8 pa0, bf16x8 pa1, bf16x8 pa2, bf16x8 pa3) {
;   const s16x4 l0 = tr_read<v_rd_off(D0, 0, 0)>(vb), h0 = tr_read<v_rd_off(D0, 0, 1)>(vb), l1 = tr_read<v_rd_off(D0, 1, 0)>(vb), h1 = tr_read<v_rd_off(D0, 1, 1)>(vb);
;   const s16x4 l2 = tr_read<v_rd_off(D0, 2, 0)>(vb), h2 = tr_read<v_rd_off(D0, 2, 1)>(vb), l3 = tr_read<v_rd_off(D0, 3, 0)>(vb), h3 = tr_read<v_rd_off(D0, 3, 1)>(vb);
;   asm volatile("s_waitcnt lgkmcnt(0)" ::: "memory"); SBAR();
;     ...
;   od = __builtin_amdgcn_mfma_f32_32x32x16_bf16(pa0, PK(l0, h0), od, 0, 0, 0);
;   od = __builtin_amdgcn_mfma_f32_32x32x16_bf16(pa1, PK(l1, h1), od, 0, 0, 0);
;   od = __builtin_amdgcn_mfma_f32_32x32x16_bf16(pa2, PK(l2, h2), od, 0, 0, 0);
;   od = __builtin_amdgcn_mfma_f32_32x32x16_bf16(pa3, PK(l3, h3), od, 0, 0, 0);
;     ...
; }
; __device__ __forceinline__ void pv_d0(f32x16* o, int vb, bf16x8 pa0, bf16x8 pa1, bf16x8 pa2, bf16x8 pa3) {
;   pv_one<0>(o[0], vb, pa0, pa1, pa2, pa3); pv_one<1>(o[1], vb, pa0, pa1, pa2, pa3); pv_one<2>(o[2], vb, pa0, pa1, pa2, pa3); pv_one<3>(o[3], vb, pa0, pa1, pa2, pa3);
.Lk_wd:
	ds_write_b128 v202, v[154:157] offset:49152
	ds_write_b128 v203, v[158:161] offset:49152
	s_waitcnt lgkmcnt(2)
	s_nop 0
	v_mfma_f32_32x32x16_bf16 v[0:15], v[162:165], v[216:219], v[0:15]
	ds_read_b64_tr_b16 v[216:217], v191 offset:0x200
	ds_read_b64_tr_b16 v[218:219], v191 offset:0xa00
	v_max_f32_e32 v232, v81, v81
	v_max_f32_e32 v233, v80, v80
	v_max_f32_e32 v232, v233, v232
	v_max3_f32 v232, v232, v82, v83
	v_max3_f32 v232, v232, v84, v85
	v_max3_f32 v232, v232, v86, v87
	v_mfma_f32_32x32x16_bf16 v[0:15], v[166:169], v[220:223], v[0:15]
	ds_read_b64_tr_b16 v[220:221], v191 offset:0x1200
	ds_read_b64_tr_b16 v[222:223], v191 offset:0x1a00
	v_max3_f32 v232, v232, v88, v89
	v_max3_f32 v232, v232, v90, v91
	v_max3_f32 v232, v232, v92, v93
	v_max3_f32 v232, v232, v94, v95
	v_max3_f32 v232, v232, v64, v65
	v_max3_f32 v232, v232, v66, v67
	v_mfma_f32_32x32x16_bf16 v[0:15], v[170:173], v[224:227], v[0:15]
	ds_read_b64_tr_b16 v[224:225], v191 offset:0x2200
	ds_read_b64_tr_b16 v[226:227], v191 offset:0x2a00
	v_max3_f32 v232, v232, v68, v69
	v_max3_f32 v232, v232, v70, v71
	v_max3_f32 v232, v232, v72, v73
	v_max3_f32 v232, v232, v74, v75
	v_max3_f32 v232, v232, v76, v77
	v_max3_f32 v232, v232, v78, v79
	v_mfma_f32_32x32x16_bf16 v[0:15], v[174:177], v[242:245], v[0:15]
	ds_read_b64_tr_b16 v[242:243], v191 offset:0x3200
	ds_read_b64_tr_b16 v[244:245], v191 offset:0x3a00
	v_mov_b32_e32 v233, v232
	s_nop 1
	v_permlane32_swap_b32_e32 v232, v233
	v_max_f32_e32 v233, v233, v233
	v_max_f32_e32 v232, v232, v232
	v_max_f32_e32 v232, v232, v233
	s_waitcnt lgkmcnt(0)
	v_mfma_f32_32x32x16_bf16 v[48:63], v[162:165], v[216:219], v[48:63]
	ds_read_b64_tr_b16 v[216:217], v191 offset:0x400
	ds_read_b64_tr_b16 v[218:219], v191 offset:0xc00
	v_sub_f32_e32 v233, v232, v210
	v_cmp_ge_f32_e32 vcc, s68, v233
	v_max_f32_e32 v233, v210, v210
	v_max_f32_e32 v232, v233, v232
	v_sub_f32_e32 v233, v210, v232
	v_mul_f32_e32 v233, 0x3e0293ee, v233
	v_mfma_f32_32x32x16_bf16 v[48:63], v[166:169], v[220:223], v[48:63]
	ds_read_b64_tr_b16 v[220:221], v191 offset:0x1400
	ds_read_b64_tr_b16 v[222:223], v191 offset:0x1c00
	s_cmp_eq_u64 vcc, exec
	s_cselect_b64 s[8:9], -1, 0
	v_exp_f32_e32 v233, v233
	v_mfma_f32_32x32x16_bf16 v[48:63], v[170:173], v[224:227], v[48:63]
	ds_read_b64_tr_b16 v[224:225], v191 offset:0x2400
	ds_read_b64_tr_b16 v[226:227], v191 offset:0x2c00
	v_cndmask_b32_e64 v210, v232, v210, s[8:9]
	v_mul_f32_e32 v250, 0xbe0293ee, v210
	v_fmamk_f32 v80, v80, 0x3e0293ee, v250
	v_fmamk_f32 v81, v81, 0x3e0293ee, v250
	v_fmamk_f32 v82, v82, 0x3e0293ee, v250
	v_fmamk_f32 v83, v83, 0x3e0293ee, v250
	v_mfma_f32_32x32x16_bf16 v[48:63], v[174:177], v[242:245], v[48:63]
	ds_read_b64_tr_b16 v[242:243], v191 offset:0x3400
	ds_read_b64_tr_b16 v[244:245], v191 offset:0x3c00
	v_fmamk_f32 v84, v84, 0x3e0293ee, v250
	v_fmamk_f32 v85, v85, 0x3e0293ee, v250
	v_fmamk_f32 v86, v86, 0x3e0293ee, v250
	v_fmamk_f32 v87, v87, 0x3e0293ee, v250
	v_fmamk_f32 v88, v88, 0x3e0293ee, v250
	v_fmamk_f32 v89, v89, 0x3e0293ee, v250
	s_waitcnt lgkmcnt(0)
	v_mfma_f32_32x32x16_bf16 v[32:47], v[162:165], v[216:219], v[32:47]
	ds_read_b64_tr_b16 v[216:217], v191 offset:0x600
	ds_read_b64_tr_b16 v[218:219], v191 offset:0xe00
	v_fmamk_f32 v90, v90, 0x3e0293ee, v250
	v_fmamk_f32 v91, v91, 0x3e0293ee, v250
	v_fmamk_f32 v92, v92, 0x3e0293ee, v250
	v_fmamk_f32 v93, v93, 0x3e0293ee, v250
	v_fmamk_f32 v94, v94, 0x3e0293ee, v250
	v_fmamk_f32 v95, v95, 0x3e0293ee, v250
	v_mfma_f32_32x32x16_bf16 v[32:47], v[166:169], v[220:223], v[32:47]
	ds_read_b64_tr_b16 v[220:221], v191 offset:0x1600
	ds_read_b64_tr_b16 v[222:223], v191 offset:0x1e00
	v_exp_f32_e32 v80, v80
	v_exp_f32_e32 v81, v81
	v_exp_f32_e32 v82, v82
	v_mfma_f32_32x32x16_bf16 v[32:47], v[170:173], v[224:227], v[32:47]
	ds_read_b64_tr_b16 v[224:225], v191 offset:0x2600
	ds_read_b64_tr_b16 v[226:227], v191 offset:0x2e00
	v_exp_f32_e32 v83, v83
	v_exp_f32_e32 v84, v84
	v_exp_f32_e32 v85, v85
	v_mfma_f32_32x32x16_bf16 v[32:47], v[174:177], v[242:245], v[32:47]
	ds_read_b64_tr_b16 v[242:243], v191 offset:0x3600
	ds_read_b64_tr_b16 v[244:245], v191 offset:0x3e00
	v_exp_f32_e32 v86, v86
	v_exp_f32_e32 v87, v87
	v_exp_f32_e32 v88, v88
	s_waitcnt lgkmcnt(0)
	v_mfma_f32_32x32x16_bf16 v[16:31], v[162:165], v[216:219], v[16:31]
	v_exp_f32_e32 v89, v89
	v_exp_f32_e32 v90, v90
	v_exp_f32_e32 v91, v91
	v_mfma_f32_32x32x16_bf16 v[16:31], v[166:169], v[220:223], v[16:31]
	v_exp_f32_e32 v92, v92
	v_exp_f32_e32 v93, v93
	v_mfma_f32_32x32x16_bf16 v[16:31], v[170:173], v[224:227], v[16:31]
	v_exp_f32_e32 v94, v94
	v_exp_f32_e32 v95, v95
	v_mfma_f32_32x32x16_bf16 v[16:31], v[174:177], v[242:245], v[16:31]
	s_barrier
	s_setprio 0
	s_waitcnt vmcnt(4)
	v_cndmask_b32_e64 v213, v233, 1.0, s[8:9]
	v_cmp_gt_f32_e32 vcc, 1.0, v213
	ds_write_b128 v204, v[146:149] offset:16384
	ds_write_b128 v205, v[150:153] offset:16384
	s_cbranch_vccz .LBB0_612
	s_and_saveexec_b64 s[18:19], s[6:7]
	ds_write_b32 v189, v213 offset:128
	s_or_b64 exec, exec, s[18:19]
	s_waitcnt lgkmcnt(0)
	v_add_u32_e32 v158, v181, v180
	ds_read_b128 v[146:149], v158 offset:224
	ds_read_b128 v[150:153], v158 offset:192
	ds_read_b128 v[154:157], v158 offset:160
	ds_read_b128 v[158:161], v158 offset:128
	s_waitcnt lgkmcnt(3)
	v_pk_mul_f32 v[12:13], v[12:13], v[146:147]
	s_waitcnt lgkmcnt(2)
	v_pk_mul_f32 v[8:9], v[8:9], v[150:151]
	s_waitcnt lgkmcnt(1)
	v_pk_mul_f32 v[4:5], v[4:5], v[154:155]
	v_pk_mul_f32 v[14:15], v[14:15], v[148:149]
	v_pk_mul_f32 v[10:11], v[10:11], v[152:153]
	v_pk_mul_f32 v[6:7], v[6:7], v[156:157]
	s_waitcnt lgkmcnt(0)
	v_pk_mul_f32 v[2:3], v[2:3], v[160:161]
	v_pk_mul_f32 v[0:1], v[0:1], v[158:159]
	v_pk_mul_f32 v[60:61], v[60:61], v[146:147]
	v_pk_mul_f32 v[56:57], v[56:57], v[150:151]
	v_pk_mul_f32 v[52:53], v[52:53], v[154:155]
	v_pk_mul_f32 v[62:63], v[62:63], v[148:149]
	v_pk_mul_f32 v[58:59], v[58:59], v[152:153]
	v_pk_mul_f32 v[54:55], v[54:55], v[156:157]
	v_pk_mul_f32 v[50:51], v[50:51], v[160:161]
	v_pk_mul_f32 v[48:49], v[48:49], v[158:159]
	v_pk_mul_f32 v[44:45], v[44:45], v[146:147]
	v_pk_mul_f32 v[40:41], v[40:41], v[150:151]
	v_pk_mul_f32 v[36:37], v[36:37], v[154:155]
	v_pk_mul_f32 v[46:47], v[46:47], v[148:149]
	v_pk_mul_f32 v[42:43], v[42:43], v[152:153]
	v_pk_mul_f32 v[38:39], v[38:39], v[156:157]
	v_pk_mul_f32 v[34:35], v[34:35], v[160:161]
	v_pk_mul_f32 v[32:33], v[32:33], v[158:159]
	v_pk_mul_f32 v[28:29], v[28:29], v[146:147]
	v_pk_mul_f32 v[24:25], v[24:25], v[150:151]
	v_pk_mul_f32 v[20:21], v[20:21], v[154:155]
	v_pk_mul_f32 v[30:31], v[30:31], v[148:149]
	v_pk_mul_f32 v[26:27], v[26:27], v[152:153]
	v_pk_mul_f32 v[22:23], v[22:23], v[156:157]
	v_pk_mul_f32 v[18:19], v[18:19], v[160:161]
	v_pk_mul_f32 v[16:17], v[16:17], v[158:159]

; #define SBAR() __builtin_amdgcn_sched_barrier(0)
; __device__ __forceinline__ void finishSM(f32x16& p0, f32x16& p1, float alpha, float& l_reg, bf16x8& pa0, bf16x8& pa1, bf16x8& pa2, bf16x8& pa3) {
;   for (int r = 0; r < 16; ++r) p1[r] = __builtin_amdgcn_exp2f(p1[r]);
;   float ps = 0; for (int r = 0; r < 16; ++r) ps += p0[r]; for (int r = 0; r < 16; ++r) ps += p1[r];
;   { auto rr = __builtin_amdgcn_permlane32_swap(__float_as_uint(ps), __float_as_uint(ps), false, false);
;     ps = __uint_as_float(rr[0]) + __uint_as_float(rr[1]); }
;   l_reg = l_reg * alpha + ps;
;     ...
;   PK4(p0, 0, pa0); PK4(p0, 8, pa1); PK4(p1, 0, pa2); PK4(p1, 8, pa3);
;     ...
; }
; __device__ __forceinline__ void qkt(f32x16& p0, f32x16& p1, const bf16* Ks, const bf16x8* qr, int r32, int hi) {
;   p0 = f32x16{}; p1 = f32x16{};
;   for (int d0 = 0; d0 < 8; ++d0) { int cb = (d0 * 16 + hi * 8) * 2;
;     bf16x8 b0 = *reinterpret_cast<const bf16x8*>((const char*)Ks + KSWZ(r32, cb));
;     bf16x8 b1 = *reinterpret_cast<const bf16x8*>((const char*)Ks + KSWZ(32 + r32, cb));
;     p0 = __builtin_amdgcn_mfma_f32_32x32x16_bf16(b0, qr[d0], p0, 0, 0, 0);
;     p1 = __builtin_amdgcn_mfma_f32_32x32x16_bf16(b1, qr[d0], p1, 0, 0, 0); }
; __device__ __forceinline__ void attn_dense_body(const bf16* __restrict__ Qb, const bf16* __restrict__ Kh, const bf16* __restrict__ Vh,
;                                                 const unsigned short* __restrict__ Gb, unsigned short* __restrict__ Yb, int seq, char* lds, const int tid) {
;     ...
;   const unsigned short* Gw = Gb + (long)(wid * QBLK) * LDG;
;   const int rsub = lane >> 4, c8 = (lane & 15) * 8;
;   u32x4 gv[8];
; #pragma unroll
;   for (int it = 0; it < 8; ++it) gv[it] = *reinterpret_cast<const u32x4*>(Gw + (long)(it * 4 + rsub) * LDG + c8);
;   SBAR(); qkt(pB0, pB1, (bf16*)((char*)K_lds + SHM_K), qr, r32, hi);
;   finishSM(pA0, pA1, alA, l_reg, pa0, pa1, pa2, pa3); SBAR();
.LBB0_614:
	s_setprio 0
	s_mul_i32 s9, s14, 0xc000
	s_mul_hi_i32 s8, s14, 0xc000
	s_add_u32 s9, s4, s9
	s_addc_u32 s8, s5, s8
	s_lshl_b32 s16, s47, 1
	s_add_u32 s9, s9, s16
	s_addc_u32 s12, s8, 0
	s_add_u32 s8, s9, 0x26401800
	s_addc_u32 s9, s12, 0
	v_mov_b64_e32 v[64:65], s[8:9]
	v_lshrrev_b32_e32 v182, 4, v208
	v_mad_i64_i32 v[64:65], s[8:9], v178, s64, v[64:65]
	v_lshlrev_b32_e32 v96, 1, v96
	v_mul_u32_u24_e32 v66, 0x6000, v182
	v_lshl_add_u64 v[64:65], v[64:65], 0, v[96:97]
	v_lshlrev_b32_e32 v66, 1, v66
	v_mov_b32_e32 v67, v97
	v_lshl_add_u64 v[68:69], v[64:65], 0, v[66:67]
	v_add_co_u32_e32 v70, vcc, s92, v68
	s_nop 1
	v_addc_co_u32_e32 v71, vcc, 0, v69, vcc
	global_load_dwordx4 v[158:161], v[68:69], off
	global_load_dwordx4 v[154:157], v[70:71], off
	v_add_co_u32_e32 v70, vcc, s94, v68
	s_nop 1
	v_addc_co_u32_e32 v71, vcc, 0, v69, vcc
	v_add_co_u32_e32 v68, vcc, s95, v68
	s_nop 1
	v_addc_co_u32_e32 v69, vcc, 0, v69, vcc
	global_load_dwordx4 v[150:153], v[70:71], off
	global_load_dwordx4 v[146:149], v[68:69], off
	v_or_b32_e32 v68, 0xc0000, v66
	v_mov_b32_e32 v69, v97
	v_lshl_add_u64 v[68:69], v[64:65], 0, v[68:69]
	v_add_u32_e32 v70, 0xf0000, v66
	v_mov_b32_e32 v71, v97
	v_lshl_add_u64 v[70:71], v[64:65], 0, v[70:71]
	global_load_dwordx4 v[142:145], v[68:69], off
	global_load_dwordx4 v[138:141], v[70:71], off
	v_add_u32_e32 v68, 0x120000, v66
	v_mov_b32_e32 v69, v97
	v_lshl_add_u64 v[68:69], v[64:65], 0, v[68:69]
	v_add_u32_e32 v66, 0x150000, v66
	v_lshl_add_u64 v[64:65], v[64:65], 0, v[66:67]
	global_load_dwordx4 v[102:105], v[68:69], off
	global_load_dwordx4 v[98:101], v[64:65], off
	ds_read_b128 v[64:67], v192 offset:49152
	ds_read_b128 v[68:71], v192 offset:57344
	s_waitcnt lgkmcnt(1)
	v_mfma_f32_32x32x16_bf16 v[80:95], v[64:67], v[126:129], 0
	s_waitcnt lgkmcnt(0)
	v_mfma_f32_32x32x16_bf16 v[64:79], v[68:71], v[126:129], 0
	ds_read_b128 v[126:129], v201 offset:49152
	ds_read_b128 v[202:205], v201 offset:57344
	s_waitcnt lgkmcnt(1)
	v_mfma_f32_32x32x16_bf16 v[80:95], v[126:129], v[122:125], v[80:95]
	s_waitcnt lgkmcnt(0)
	v_mfma_f32_32x32x16_bf16 v[64:79], v[202:205], v[122:125], v[64:79]
	ds_read_b128 v[122:125], v200 offset:49152
	ds_read_b128 v[126:129], v200 offset:57344
	s_waitcnt lgkmcnt(1)
	v_mfma_f32_32x32x16_bf16 v[80:95], v[122:125], v[134:137], v[80:95]
	s_waitcnt lgkmcnt(0)
	v_mfma_f32_32x32x16_bf16 v[64:79], v[126:129], v[134:137], v[64:79]
	ds_read_b128 v[122:125], v195 offset:49152
	ds_read_b128 v[126:129], v195 offset:57344
	s_waitcnt lgkmcnt(1)
	v_mfma_f32_32x32x16_bf16 v[80:95], v[122:125], v[130:133], v[80:95]
	s_waitcnt lgkmcnt(0)
	v_mfma_f32_32x32x16_bf16 v[64:79], v[126:129], v[130:133], v[64:79]
	ds_read_b128 v[122:125], v194 offset:49152
	ds_read_b128 v[126:129], v194 offset:57344
	v_exp_f32_e32 v130, v162
	v_exp_f32_e32 v131, v163
	s_waitcnt lgkmcnt(1)
	v_mfma_f32_32x32x16_bf16 v[80:95], v[122:125], v[118:121], v[80:95]
	s_waitcnt lgkmcnt(0)
	v_mfma_f32_32x32x16_bf16 v[64:79], v[126:129], v[118:121], v[64:79]
	ds_read_b128 v[118:121], v193 offset:49152
	ds_read_b128 v[122:125], v193 offset:57344
	v_exp_f32_e32 v126, v172
	v_exp_f32_e32 v127, v173
	v_exp_f32_e32 v128, v168
	v_exp_f32_e32 v129, v169
	s_waitcnt lgkmcnt(1)
	v_mfma_f32_32x32x16_bf16 v[80:95], v[118:121], v[114:117], v[80:95]
	s_waitcnt lgkmcnt(0)
	v_mfma_f32_32x32x16_bf16 v[64:79], v[122:125], v[114:117], v[64:79]
	ds_read_b128 v[114:117], v207 offset:49152
	ds_read_b128 v[118:121], v207 offset:57344
	v_exp_f32_e32 v122, v166
	v_exp_f32_e32 v123, v167
	v_exp_f32_e32 v124, v164
	v_exp_f32_e32 v125, v165
	s_waitcnt lgkmcnt(1)
	v_mfma_f32_32x32x16_bf16 v[80:95], v[114:117], v[110:113], v[80:95]
	s_waitcnt lgkmcnt(0)
	v_mfma_f32_32x32x16_bf16 v[64:79], v[118:121], v[110:113], v[64:79]
	ds_read_b128 v[110:113], v206 offset:49152
	ds_read_b128 v[114:117], v206 offset:57344
	v_exp_f32_e32 v118, v174
	v_exp_f32_e32 v119, v175
	v_exp_f32_e32 v120, v170
	v_exp_f32_e32 v121, v171
	s_waitcnt lgkmcnt(1)
	v_mfma_f32_32x32x16_bf16 v[80:95], v[110:113], v[106:109], v[80:95]
	v_cvt_pk_bf16_f32 v110, v229, v230
	v_cvt_pk_bf16_f32 v111, v226, v228
	v_cvt_pk_bf16_f32 v112, v215, v217
	v_cvt_pk_bf16_f32 v113, v219, v221
	s_waitcnt lgkmcnt(0)
	v_mfma_f32_32x32x16_bf16 v[64:79], v[114:117], v[106:109], v[64:79]
	v_add_f32_e32 v106, 0, v223
	v_add_f32_e32 v106, v224, v106
	v_add_f32_e32 v106, v225, v106
	v_add_f32_e32 v106, v227, v106
	v_add_f32_e32 v106, v229, v106
	v_add_f32_e32 v106, v230, v106
	v_add_f32_e32 v106, v226, v106
	v_add_f32_e32 v106, v228, v106
	v_add_f32_e32 v106, v215, v106
	v_add_f32_e32 v106, v217, v106
	v_add_f32_e32 v106, v219, v106
	v_add_f32_e32 v106, v221, v106
	v_exp_f32_e32 v116, v176
	v_add_f32_e32 v106, v216, v106
	v_exp_f32_e32 v117, v177
	v_add_f32_e32 v106, v218, v106
	v_add_f32_e32 v106, v220, v106
	v_add_f32_e32 v106, v222, v106
	v_add_f32_e32 v106, v116, v106
	v_add_f32_e32 v106, v117, v106
	v_add_f32_e32 v106, v118, v106
	v_add_f32_e32 v106, v119, v106
	v_add_f32_e32 v106, v120, v106
	v_add_f32_e32 v106, v121, v106
	v_add_f32_e32 v106, v122, v106
	v_add_f32_e32 v106, v123, v106
	v_add_f32_e32 v106, v124, v106
	v_add_f32_e32 v106, v125, v106
	v_add_f32_e32 v106, v126, v106
	v_add_f32_e32 v106, v127, v106
	v_add_f32_e32 v106, v128, v106
	v_add_f32_e32 v106, v129, v106
	v_add_f32_e32 v106, v130, v106
	v_add_f32_e32 v106, v131, v106
	v_mov_b32_e32 v107, v106
	v_cvt_pk_bf16_f32 v108, v223, v224
	v_cvt_pk_bf16_f32 v109, v225, v227
	v_permlane32_swap_b32_e32 v106, v107
	v_permlane32_swap_b32_e32 v108, v110
	v_permlane32_swap_b32_e32 v109, v111
	v_cvt_pk_bf16_f32 v114, v216, v218
	v_cvt_pk_bf16_f32 v115, v220, v222
	v_cvt_pk_bf16_f32 v116, v116, v117
	v_cvt_pk_bf16_f32 v117, v118, v119
	v_cvt_pk_bf16_f32 v118, v120, v121
	v_cvt_pk_bf16_f32 v119, v122, v123
	v_cvt_pk_bf16_f32 v120, v124, v125
	v_cvt_pk_bf16_f32 v121, v126, v127
	v_cvt_pk_bf16_f32 v122, v128, v129
	v_cvt_pk_bf16_f32 v123, v130, v131
	v_permlane32_swap_b32_e32 v112, v114
	v_permlane32_swap_b32_e32 v113, v115
	v_permlane32_swap_b32_e32 v116, v118
	v_permlane32_swap_b32_e32 v117, v119
	v_permlane32_swap_b32_e32 v120, v122
	v_permlane32_swap_b32_e32 v121, v123
	ds_read_b64_tr_b16 v[124:125], v179 offset:0
	ds_read_b64_tr_b16 v[126:127], v179 offset:0x800
	ds_read_b64_tr_b16 v[128:129], v179 offset:0x1000
	ds_read_b64_tr_b16 v[130:131], v179 offset:0x1800
	ds_read_b64_tr_b16 v[132:133], v179 offset:0x2000
	ds_read_b64_tr_b16 v[134:135], v179 offset:0x2800
	ds_read_b64_tr_b16 v[162:163], v179 offset:0x3000
	ds_read_b64_tr_b16 v[164:165], v179 offset:0x3800
	s_waitcnt lgkmcnt(0)
; #define SBAR() __builtin_amdgcn_sched_barrier(0)
; __device__ __forceinline__ void partialSM(f32x16& p0, f32x16& p1, float& m_reg, float& mn, float& alpha) {
;   constexpr float C = SCALE * 1.4426950408889634f;
;   float pmax = p0[0]; for (int r = 1; r < 16; ++r) pmax = fmaxf(pmax, p0[r]); for (int r = 0; r < 16; ++r) pmax = fmaxf(pmax, p1[r]);
;   { auto rr = __builtin_amdgcn_permlane32_swap(__float_as_uint(pmax), __float_as_uint(pmax), false, false);
;     pmax = fmaxf(__uint_as_float(rr[0]), __uint_as_float(rr[1])); }
;   if (__builtin_expect(__all(pmax - m_reg <= THR / SCALE), 1)) { mn = m_reg; alpha = 1.f; }
;   else { mn = fmaxf(m_reg, pmax); alpha = __builtin_amdgcn_exp2f((m_reg - mn) * C); m_reg = mn; }
;   float mnC = -mn * C;
;   for (int r = 0; r < 16; ++r) p0[r] = fmaf(p0[r], C, mnC); for (int r = 0; r < 16; ++r) p1[r] = fmaf(p1[r], C, mnC);
;   for (int r = 0; r < 16; ++r) p0[r] = __builtin_amdgcn_exp2f(p0[r]);
; template <int D0> __device__ __forceinline__ void pv_one(f32x16& od, int vb, bf16x8 pa0, bf16x8 pa1, bf16x8 pa2, bf16x8 pa3) {
;   const s16x4 l0 = tr_read<v_rd_off(D0, 0, 0)>(vb), h0 = tr_read<v_rd_off(D0, 0, 1)>(vb), l1 = tr_read<v_rd_off(D0, 1, 0)>(vb), h1 = tr_read<v_rd_off(D0, 1, 1)>(vb);
;   const s16x4 l2 = tr_read<v_rd_off(D0, 2, 0)>(vb), h2 = tr_read<v_rd_off(D0, 2, 1)>(vb), l3 = tr_read<v_rd_off(D0, 3, 0)>(vb), h3 = tr_read<v_rd_off(D0, 3, 1)>(vb);
;   asm volatile("s_waitcnt lgkmcnt(0)" ::: "memory"); SBAR();
;     ...
;   od = __builtin_amdgcn_mfma_f32_32x32x16_bf16(pa0, PK(l0, h0), od, 0, 0, 0);
;   od = __builtin_amdgcn_mfma_f32_32x32x16_bf16(pa1, PK(l1, h1), od, 0, 0, 0);
;   od = __builtin_amdgcn_mfma_f32_32x32x16_bf16(pa2, PK(l2, h2), od, 0, 0, 0);
;   od = __builtin_amdgcn_mfma_f32_32x32x16_bf16(pa3, PK(l3, h3), od, 0, 0, 0);
;     ...
; }
; __device__ __forceinline__ void pv_d0(f32x16* o, int vb, bf16x8 pa0, bf16x8 pa1, bf16x8 pa2, bf16x8 pa3) {
;   pv_one<0>(o[0], vb, pa0, pa1, pa2, pa3); pv_one<1>(o[1], vb, pa0, pa1, pa2, pa3); pv_one<2>(o[2], vb, pa0, pa1, pa2, pa3); pv_one<3>(o[3], vb, pa0, pa1, pa2, pa3);
	s_nop 0
	v_mfma_f32_32x32x16_bf16 v[0:15], v[108:111], v[124:127], v[0:15]
	ds_read_b64_tr_b16 v[124:125], v179 offset:0x200
	ds_read_b64_tr_b16 v[126:127], v179 offset:0xa00
	v_mfma_f32_32x32x16_bf16 v[0:15], v[112:115], v[128:131], v[0:15]
	ds_read_b64_tr_b16 v[128:129], v179 offset:0x1200
	ds_read_b64_tr_b16 v[130:131], v179 offset:0x1a00
	v_mfma_f32_32x32x16_bf16 v[0:15], v[116:119], v[132:135], v[0:15]
	ds_read_b64_tr_b16 v[132:133], v179 offset:0x2200
	ds_read_b64_tr_b16 v[134:135], v179 offset:0x2a00
	v_mfma_f32_32x32x16_bf16 v[0:15], v[120:123], v[162:165], v[0:15]
	ds_read_b64_tr_b16 v[162:163], v179 offset:0x3200
	ds_read_b64_tr_b16 v[164:165], v179 offset:0x3a00
	s_waitcnt lgkmcnt(0)
	v_mfma_f32_32x32x16_bf16 v[48:63], v[108:111], v[124:127], v[48:63]
	ds_read_b64_tr_b16 v[124:125], v179 offset:0x400
	ds_read_b64_tr_b16 v[126:127], v179 offset:0xc00
	v_mfma_f32_32x32x16_bf16 v[48:63], v[112:115], v[128:131], v[48:63]
	ds_read_b64_tr_b16 v[128:129], v179 offset:0x1400
	ds_read_b64_tr_b16 v[130:131], v179 offset:0x1c00
	v_mfma_f32_32x32x16_bf16 v[48:63], v[116:119], v[132:135], v[48:63]
	ds_read_b64_tr_b16 v[132:133], v179 offset:0x2400
	ds_read_b64_tr_b16 v[134:135], v179 offset:0x2c00
	v_mfma_f32_32x32x16_bf16 v[48:63], v[120:123], v[162:165], v[48:63]
	ds_read_b64_tr_b16 v[162:163], v179 offset:0x3400
	ds_read_b64_tr_b16 v[164:165], v179 offset:0x3c00
	s_waitcnt lgkmcnt(0)
	v_mfma_f32_32x32x16_bf16 v[32:47], v[108:111], v[124:127], v[32:47]
	ds_read_b64_tr_b16 v[124:125], v179 offset:0x600
	ds_read_b64_tr_b16 v[126:127], v179 offset:0xe00
	v_mfma_f32_32x32x16_bf16 v[32:47], v[112:115], v[128:131], v[32:47]
	ds_read_b64_tr_b16 v[128:129], v179 offset:0x1600
	ds_read_b64_tr_b16 v[130:131], v179 offset:0x1e00
	v_mfma_f32_32x32x16_bf16 v[32:47], v[116:119], v[132:135], v[32:47]
	ds_read_b64_tr_b16 v[132:133], v179 offset:0x2600
	ds_read_b64_tr_b16 v[134:135], v179 offset:0x2e00
	v_mfma_f32_32x32x16_bf16 v[32:47], v[120:123], v[162:165], v[32:47]
	ds_read_b64_tr_b16 v[162:163], v179 offset:0x3600
	ds_read_b64_tr_b16 v[164:165], v179 offset:0x3e00
	s_waitcnt lgkmcnt(0)
	v_mfma_f32_32x32x16_bf16 v[16:31], v[108:111], v[124:127], v[16:31]
	v_max_f32_e32 v108, v81, v81
	v_max_f32_e32 v109, v80, v80
	v_max_f32_e32 v108, v109, v108
	v_max3_f32 v108, v108, v82, v83
	v_max3_f32 v108, v108, v84, v85
	v_max3_f32 v108, v108, v86, v87
	v_max3_f32 v108, v108, v88, v89
	v_max3_f32 v108, v108, v90, v91
	v_max3_f32 v108, v108, v92, v93
	v_mfma_f32_32x32x16_bf16 v[16:31], v[112:115], v[128:131], v[16:31]
	v_max3_f32 v108, v108, v94, v95
	v_max3_f32 v108, v108, v64, v65
	v_max3_f32 v108, v108, v66, v67
	v_max3_f32 v108, v108, v68, v69
	v_max3_f32 v108, v108, v70, v71
	v_max3_f32 v108, v108, v72, v73
	v_max3_f32 v108, v108, v74, v75
	v_max3_f32 v108, v108, v76, v77
	v_mfma_f32_32x32x16_bf16 v[16:31], v[116:119], v[132:135], v[16:31]
	v_max3_f32 v108, v108, v78, v79
	v_mov_b32_e32 v109, v108
	s_nop 1
	v_permlane32_swap_b32_e32 v108, v109
	v_max_f32_e32 v109, v109, v109
	v_max_f32_e32 v108, v108, v108
	v_max_f32_e32 v108, v108, v109
	v_sub_f32_e32 v109, v108, v210
	v_cmp_ge_f32_e32 vcc, s68, v109
	v_max_f32_e32 v109, v210, v210
	v_max_f32_e32 v109, v109, v108
	v_mfma_f32_32x32x16_bf16 v[16:31], v[120:123], v[162:165], v[16:31]
	v_sub_f32_e32 v108, v210, v109
	v_mul_f32_e32 v108, 0x3e0293ee, v108
	v_exp_f32_e32 v108, v108
	s_cmp_eq_u64 vcc, exec
	s_cselect_b64 s[8:9], -1, 0
	v_cndmask_b32_e64 v108, v108, 1.0, s[8:9]
	v_cmp_gt_f32_e32 vcc, 1.0, v108
	s_barrier
	s_cbranch_vccz .LBB0_618
	s_and_saveexec_b64 s[12:13], s[6:7]
	ds_write_b32 v189, v108 offset:128
	s_or_b64 exec, exec, s[12:13]
	s_waitcnt lgkmcnt(0)
	v_add_u32_e32 v122, v181, v180
	ds_read_b128 v[110:113], v122 offset:224
	ds_read_b128 v[114:117], v122 offset:192
	ds_read_b128 v[118:121], v122 offset:160
	ds_read_b128 v[122:125], v122 offset:128
	s_waitcnt lgkmcnt(3)
	v_pk_mul_f32 v[12:13], v[12:13], v[110:111]
	s_waitcnt lgkmcnt(2)
	v_pk_mul_f32 v[8:9], v[8:9], v[114:115]
	s_waitcnt lgkmcnt(1)
	v_pk_mul_f32 v[4:5], v[4:5], v[118:119]
	v_pk_mul_f32 v[14:15], v[14:15], v[112:113]
	v_pk_mul_f32 v[10:11], v[10:11], v[116:117]
	v_pk_mul_f32 v[6:7], v[6:7], v[120:121]
	s_waitcnt lgkmcnt(0)
	v_pk_mul_f32 v[2:3], v[2:3], v[124:125]
	v_pk_mul_f32 v[0:1], v[0:1], v[122:123]
	v_pk_mul_f32 v[60:61], v[60:61], v[110:111]
	v_pk_mul_f32 v[56:57], v[56:57], v[114:115]
	v_pk_mul_f32 v[52:53], v[52:53], v[118:119]
	v_pk_mul_f32 v[62:63], v[62:63], v[112:113]
	v_pk_mul_f32 v[58:59], v[58:59], v[116:117]
	v_pk_mul_f32 v[54:55], v[54:55], v[120:121]
	v_pk_mul_f32 v[50:51], v[50:51], v[124:125]
	v_pk_mul_f32 v[48:49], v[48:49], v[122:123]
	v_pk_mul_f32 v[44:45], v[44:45], v[110:111]
	v_pk_mul_f32 v[40:41], v[40:41], v[114:115]
	v_pk_mul_f32 v[36:37], v[36:37], v[118:119]
	v_pk_mul_f32 v[46:47], v[46:47], v[112:113]
	v_pk_mul_f32 v[42:43], v[42:43], v[116:117]
	v_pk_mul_f32 v[38:39], v[38:39], v[120:121]
	v_pk_mul_f32 v[34:35], v[34:35], v[124:125]
	v_pk_mul_f32 v[32:33], v[32:33], v[122:123]
	v_pk_mul_f32 v[28:29], v[28:29], v[110:111]
	v_pk_mul_f32 v[24:25], v[24:25], v[114:115]
	v_pk_mul_f32 v[20:21], v[20:21], v[118:119]
	v_pk_mul_f32 v[30:31], v[30:31], v[112:113]
	v_pk_mul_f32 v[26:27], v[26:27], v[116:117]
	v_pk_mul_f32 v[22:23], v[22:23], v[120:121]
	v_pk_mul_f32 v[18:19], v[18:19], v[124:125]
	v_pk_mul_f32 v[16:17], v[16:17], v[122:123]
